# diff-attention loop: each LDS-fragment s_waitcnt placed right after the slot's ds_read (ahead of the row-sum adds) so no wait sits between the last filler and the next MFMA
# speedup vs baseline: 1.0012x; 1.0012x over previous
; #define ATT_LAS __attribute__((address_space(3)))
; #define SB0() __builtin_amdgcn_sched_barrier(0)
; __device__ __forceinline__ void hs_fast(f32x16& S, f32x16 (&O)[4], bf16x8 (&pf)[2], float& lsum, const bf16x8 (&qf)[4], const ATT_LAS unsigned char* ka, const ATT_LAS unsigned char* va) {
;     bf16x8 kf[4], vf[8]; f32x16 N; float acc;
;     const f32x16 Z = {0.f, 0.f, 0.f, 0.f, 0.f, 0.f, 0.f, 0.f, 0.f, 0.f, 0.f, 0.f, 0.f, 0.f, 0.f, 0.f};
;     kf[0] = LDF(ka); kf[1] = LDF(ka + 32); kf[2] = LDF(ka + 64); kf[3] = LDF(ka + 96);
;     vf[0] = LDF(va); vf[1] = LDF(va + 32 * VPITCH); vf[2] = LDF(va + 64 * VPITCH); vf[3] = LDF(va + 96 * VPITCH);
;     SB0();
;     N = MFMA32(kf[0], qf[0], Z);          S[0] = EX2(S[0]); S[1] = EX2(S[1]);
;     SB0();
;     O[0] = MFMA32(vf[0], pf[0], O[0]);    S[2] = EX2(S[2]); S[3] = EX2(S[3]); acc = S[0] + S[1];
;     SB0();
;     N = MFMA32(kf[1], qf[1], N);          S[4] = EX2(S[4]); S[5] = EX2(S[5]); acc += S[2]; acc += S[3];
;     SB0();
;     O[1] = MFMA32(vf[1], pf[0], O[1]);    S[6] = EX2(S[6]); S[7] = EX2(S[7]); acc += S[4]; acc += S[5];
;     SB0();
;     N = MFMA32(kf[2], qf[2], N);          S[8] = EX2(S[8]); S[9] = EX2(S[9]); acc += S[6]; acc += S[7];
;     vf[4] = LDF(va + 32); vf[5] = LDF(va + 32 * VPITCH + 32);
;     SB0();
;     O[2] = MFMA32(vf[2], pf[0], O[2]);    S[10] = EX2(S[10]); S[11] = EX2(S[11]); acc += S[8]; acc += S[9];
;     vf[6] = LDF(va + 64 * VPITCH + 32); vf[7] = LDF(va + 96 * VPITCH + 32);
;     SB0();
;     N = MFMA32(kf[3], qf[3], N);          S[12] = EX2(S[12]); S[13] = EX2(S[13]); acc += S[10]; acc += S[11];
;     SB0();
;     O[3] = MFMA32(vf[3], pf[0], O[3]);    S[14] = EX2(S[14]); S[15] = EX2(S[15]); acc += S[12]; acc += S[13];
;     SB0();
;     u32x4 w0, w1;
;     O[0] = MFMA32(vf[4], pf[1], O[0]);    w0.x = cvt_pk_bf16(S[0], S[1]); w0.y = cvt_pk_bf16(S[2], S[3]); acc += S[14]; acc += S[15];
;     SB0();
;     O[1] = MFMA32(vf[5], pf[1], O[1]);    w0.z = cvt_pk_bf16(S[4], S[5]); w0.w = cvt_pk_bf16(S[6], S[7]);
;     SB0();
;     O[2] = MFMA32(vf[6], pf[1], O[2]);    w1.x = cvt_pk_bf16(S[8], S[9]); w1.y = cvt_pk_bf16(S[10], S[11]);
;     SB0();
;     O[3] = MFMA32(vf[7], pf[1], O[3]);    w1.z = cvt_pk_bf16(S[12], S[13]); w1.w = cvt_pk_bf16(S[14], S[15]);
;     SB0();
;     lsum += acc; pf[0] = __builtin_bit_cast(bf16x8, w0); pf[1] = __builtin_bit_cast(bf16x8, w1); S = N;
; }
.Lfa_even:
	v_mov_b32_e32 v15, v1
	v_add_u32_e32 v1, s99, v196
	s_waitcnt lgkmcnt(9)
	v_mfma_f32_32x32x16_bf16 v[96:111], v[218:221], v[112:115], 0
	v_exp_f32_e32 v80, v80
	v_exp_f32_e32 v81, v81
	ds_read_b128 v[218:221], v14 offset:8800
	s_waitcnt lgkmcnt(8)
	v_add_f32_e32 v244, v80, v81
	v_mfma_f32_32x32x16_bf16 v[64:79], v[222:225], v[144:147], v[64:79]
	v_exp_f32_e32 v82, v82
	v_exp_f32_e32 v83, v83
	ds_read_b128 v[222:225], v15 offset:31296
	s_waitcnt lgkmcnt(7)
	v_add_f32_e32 v245, v82, v83
	v_mfma_f32_32x32x16_bf16 v[96:111], v[226:229], v[116:119], v[96:111]
	v_exp_f32_e32 v84, v84
	v_exp_f32_e32 v85, v85
	ds_read_b128 v[226:229], v15 offset:17504
	s_waitcnt lgkmcnt(6)
	v_add_f32_e32 v244, v244, v84
	v_add_f32_e32 v245, v245, v85
	v_mfma_f32_32x32x16_bf16 v[48:63], v[230:233], v[144:147], v[48:63]
	v_exp_f32_e32 v86, v86
	v_exp_f32_e32 v87, v87
	ds_read_b128 v[230:233], v15 offset:22112
	s_waitcnt lgkmcnt(5)
	v_add_f32_e32 v244, v244, v86
	v_add_f32_e32 v245, v245, v87
	v_mfma_f32_32x32x16_bf16 v[96:111], v[234:237], v[120:123], v[96:111]
	v_exp_f32_e32 v88, v88
	v_exp_f32_e32 v89, v89
	ds_read_b128 v[234:237], v15 offset:26720
	s_waitcnt lgkmcnt(5)
	v_add_f32_e32 v244, v244, v88
	v_add_f32_e32 v245, v245, v89
	v_mfma_f32_32x32x16_bf16 v[32:47], v[2:5], v[144:147], v[32:47]
	v_exp_f32_e32 v90, v90
	v_exp_f32_e32 v91, v91
	ds_read_b128 v[2:5], v15 offset:31328
	s_waitcnt lgkmcnt(5)
	v_add_f32_e32 v244, v244, v90
	v_add_f32_e32 v245, v245, v91
	v_mfma_f32_32x32x16_bf16 v[96:111], v[218:221], v[124:127], v[96:111]
	v_exp_f32_e32 v92, v92
	v_exp_f32_e32 v93, v93
	ds_read_b128 v[218:221], v1 offset:17408
	s_waitcnt lgkmcnt(5)
	v_add_f32_e32 v244, v244, v92
	v_add_f32_e32 v245, v245, v93
	v_mfma_f32_32x32x16_bf16 v[16:31], v[222:225], v[144:147], v[16:31]
	v_exp_f32_e32 v94, v94
	v_exp_f32_e32 v95, v95
	ds_read_b128 v[222:225], v1 offset:22016
	s_waitcnt lgkmcnt(5)
	v_add_f32_e32 v244, v244, v94
	v_add_f32_e32 v245, v245, v95
	v_mfma_f32_32x32x16_bf16 v[64:79], v[226:229], v[150:153], v[64:79]
	v_add_f32_e32 v161, v161, v244
	v_cvt_pk_bf16_f32 v6, v80, v81
	v_cvt_pk_bf16_f32 v7, v82, v83
	ds_read_b128 v[226:229], v1 offset:26624
	s_waitcnt lgkmcnt(5)
	v_mfma_f32_32x32x16_bf16 v[48:63], v[230:233], v[150:153], v[48:63]
	v_add_f32_e32 v161, v161, v245
	v_cvt_pk_bf16_f32 v8, v84, v85
	v_cvt_pk_bf16_f32 v9, v86, v87
	ds_read_b128 v[230:233], v1 offset:31232
	s_waitcnt lgkmcnt(5)
	v_mfma_f32_32x32x16_bf16 v[32:47], v[234:237], v[150:153], v[32:47]
	v_cvt_pk_bf16_f32 v10, v88, v89
	v_cvt_pk_bf16_f32 v11, v90, v91
	s_waitcnt lgkmcnt(4)
	v_mfma_f32_32x32x16_bf16 v[16:31], v[2:5], v[150:153], v[16:31]
	v_cvt_pk_bf16_f32 v12, v92, v93
	v_cvt_pk_bf16_f32 v13, v94, v95
	ds_read_b128 v[2:5], v1 offset:17440
	s_add_i32 s46, s46, 1
	s_cmp_eq_u32 s46, s24
	s_cbranch_scc1 .Lfa_exit_even
	s_cmp_eq_u32 s41, 0
	s_cbranch_scc0 .Lfa_odd_b
	s_barrier
	v_add_u32_e32 v14, s100, v163
	ds_read_b128 v[234:237], v14
	v_add_u32_e32 v246, s98, v193
	v_add_u32_e32 v247, s98, v194
	s_waitcnt lgkmcnt(5)
	v_mfma_f32_32x32x16_bf16 v[64:79], v[218:221], v[6:9], v[64:79]
	v_exp_f32_e32 v96, v96
	v_exp_f32_e32 v97, v97
	ds_read_b128 v[218:221], v14 offset:32
	s_waitcnt lgkmcnt(5)
	v_add_f32_e32 v244, v96, v97
	v_mfma_f32_32x32x16_bf16 v[48:63], v[222:225], v[6:9], v[48:63]
	v_exp_f32_e32 v98, v98
	v_exp_f32_e32 v99, v99
	ds_read_b128 v[222:225], v1 offset:22048
	s_waitcnt lgkmcnt(5)
	v_add_f32_e32 v245, v98, v99
	v_mfma_f32_32x32x16_bf16 v[32:47], v[226:229], v[6:9], v[32:47]
	v_exp_f32_e32 v100, v100
	v_exp_f32_e32 v101, v101
	ds_read_b128 v[226:229], v14 offset:64
	s_waitcnt lgkmcnt(5)
	v_add_f32_e32 v244, v244, v100
	v_add_f32_e32 v245, v245, v101
	v_mfma_f32_32x32x16_bf16 v[16:31], v[230:233], v[6:9], v[16:31]
	v_exp_f32_e32 v102, v102
	v_exp_f32_e32 v103, v103
	ds_read_b128 v[230:233], v1 offset:26656
	s_waitcnt lgkmcnt(4)
	v_add_f32_e32 v244, v244, v102
	v_add_f32_e32 v245, v245, v103
	v_mfma_f32_32x32x16_bf16 v[80:95], v[234:237], v[112:115], 0
	v_exp_f32_e32 v104, v104
	v_exp_f32_e32 v105, v105
	ds_read_b128 v[234:237], v14 offset:96
	s_waitcnt lgkmcnt(5)
	v_add_f32_e32 v244, v244, v104
	v_add_f32_e32 v245, v245, v105
	v_mfma_f32_32x32x16_bf16 v[64:79], v[2:5], v[10:13], v[64:79]
	v_exp_f32_e32 v106, v106
	v_exp_f32_e32 v107, v107
	ds_read_b128 v[2:5], v1 offset:31264
	s_waitcnt lgkmcnt(5)
	v_add_f32_e32 v244, v244, v106
	v_add_f32_e32 v245, v245, v107
	v_mfma_f32_32x32x16_bf16 v[80:95], v[218:221], v[116:119], v[80:95]
	v_exp_f32_e32 v108, v108
	v_exp_f32_e32 v109, v109
	ds_read_b128 v[218:221], v14 offset:8704
	v_add_f32_e32 v244, v244, v108
	v_add_f32_e32 v245, v245, v109
	s_waitcnt vmcnt(0)
	ds_write_b128 v246, v[128:131]
	s_waitcnt lgkmcnt(6)
	v_mfma_f32_32x32x16_bf16 v[48:63], v[222:225], v[10:13], v[48:63]
	v_exp_f32_e32 v110, v110
	v_exp_f32_e32 v111, v111
	ds_read_b128 v[222:225], v1 offset:17472
	v_add_f32_e32 v244, v244, v110
	v_add_f32_e32 v245, v245, v111
	ds_write_b128 v247, v[132:135] offset:17408
	s_waitcnt lgkmcnt(7)
	v_mfma_f32_32x32x16_bf16 v[80:95], v[226:229], v[120:123], v[80:95]
	v_add_f32_e32 v161, v161, v244
	v_cvt_pk_bf16_f32 v144, v96, v97
	v_cvt_pk_bf16_f32 v145, v98, v99
	ds_read_b128 v[226:229], v14 offset:8736
	ds_write_b128 v246, v[136:139] offset:8704
	s_waitcnt lgkmcnt(8)
	v_mfma_f32_32x32x16_bf16 v[32:47], v[230:233], v[10:13], v[32:47]
	v_add_f32_e32 v161, v161, v245
	v_cvt_pk_bf16_f32 v146, v100, v101
	v_cvt_pk_bf16_f32 v147, v102, v103
	ds_read_b128 v[230:233], v1 offset:22080
	ds_write_b128 v247, v[140:143] offset:26624
	s_waitcnt lgkmcnt(9)
	v_mfma_f32_32x32x16_bf16 v[80:95], v[234:237], v[124:127], v[80:95]
	v_cvt_pk_bf16_f32 v150, v104, v105
	v_cvt_pk_bf16_f32 v151, v106, v107
	ds_read_b128 v[234:237], v14 offset:8768
	s_cmp_ge_u32 s47, s23
	s_cbranch_scc1 .Lfa_noload
	s_lshl_b32 s48, s47, 17
	s_lshl_b32 s4, s47, 7
	s_add_u32 s48, s20, s48
	s_addc_u32 s49, s21, 0
	global_load_dwordx4 v[128:131], v240, s[48:49]
	s_add_u32 s4, s12, s4
	s_addc_u32 s25, s13, 0
	s_mov_b32 s5, s25
	global_load_dwordx4 v[132:135], v242, s[4:5]
	global_load_dwordx4 v[136:139], v241, s[48:49]
	global_load_dwordx4 v[140:143], v243, s[4:5]
	s_mov_b32 s5, 0

; #define ATT_LAS __attribute__((address_space(3)))
; #define SB0() __builtin_amdgcn_sched_barrier(0)
; __device__ __forceinline__ void hs_fast(f32x16& S, f32x16 (&O)[4], bf16x8 (&pf)[2], float& lsum, const bf16x8 (&qf)[4], const ATT_LAS unsigned char* ka, const ATT_LAS unsigned char* va) {
;     bf16x8 kf[4], vf[8]; f32x16 N; float acc;
;     const f32x16 Z = {0.f, 0.f, 0.f, 0.f, 0.f, 0.f, 0.f, 0.f, 0.f, 0.f, 0.f, 0.f, 0.f, 0.f, 0.f, 0.f};
;     kf[0] = LDF(ka); kf[1] = LDF(ka + 32); kf[2] = LDF(ka + 64); kf[3] = LDF(ka + 96);
;     vf[0] = LDF(va); vf[1] = LDF(va + 32 * VPITCH); vf[2] = LDF(va + 64 * VPITCH); vf[3] = LDF(va + 96 * VPITCH);
;     SB0();
;     N = MFMA32(kf[0], qf[0], Z);          S[0] = EX2(S[0]); S[1] = EX2(S[1]);
;     SB0();
;     O[0] = MFMA32(vf[0], pf[0], O[0]);    S[2] = EX2(S[2]); S[3] = EX2(S[3]); acc = S[0] + S[1];
;     SB0();
;     N = MFMA32(kf[1], qf[1], N);          S[4] = EX2(S[4]); S[5] = EX2(S[5]); acc += S[2]; acc += S[3];
;     SB0();
;     O[1] = MFMA32(vf[1], pf[0], O[1]);    S[6] = EX2(S[6]); S[7] = EX2(S[7]); acc += S[4]; acc += S[5];
;     SB0();
;     N = MFMA32(kf[2], qf[2], N);          S[8] = EX2(S[8]); S[9] = EX2(S[9]); acc += S[6]; acc += S[7];
;     vf[4] = LDF(va + 32); vf[5] = LDF(va + 32 * VPITCH + 32);
;     SB0();
;     O[2] = MFMA32(vf[2], pf[0], O[2]);    S[10] = EX2(S[10]); S[11] = EX2(S[11]); acc += S[8]; acc += S[9];
;     vf[6] = LDF(va + 64 * VPITCH + 32); vf[7] = LDF(va + 96 * VPITCH + 32);
;     SB0();
;     N = MFMA32(kf[3], qf[3], N);          S[12] = EX2(S[12]); S[13] = EX2(S[13]); acc += S[10]; acc += S[11];
;     SB0();
;     O[3] = MFMA32(vf[3], pf[0], O[3]);    S[14] = EX2(S[14]); S[15] = EX2(S[15]); acc += S[12]; acc += S[13];
;     SB0();
;     u32x4 w0, w1;
;     O[0] = MFMA32(vf[4], pf[1], O[0]);    w0.x = cvt_pk_bf16(S[0], S[1]); w0.y = cvt_pk_bf16(S[2], S[3]); acc += S[14]; acc += S[15];
;     SB0();
;     O[1] = MFMA32(vf[5], pf[1], O[1]);    w0.z = cvt_pk_bf16(S[4], S[5]); w0.w = cvt_pk_bf16(S[6], S[7]);
;     SB0();
;     O[2] = MFMA32(vf[6], pf[1], O[2]);    w1.x = cvt_pk_bf16(S[8], S[9]); w1.y = cvt_pk_bf16(S[10], S[11]);
;     SB0();
;     O[3] = MFMA32(vf[7], pf[1], O[3]);    w1.z = cvt_pk_bf16(S[12], S[13]); w1.w = cvt_pk_bf16(S[14], S[15]);
;     SB0();
;     lsum += acc; pf[0] = __builtin_bit_cast(bf16x8, w0); pf[1] = __builtin_bit_cast(bf16x8, w1); S = N;
; }
.Lfa_odd_b:
	s_waitcnt lgkmcnt(4)
	v_mfma_f32_32x32x16_bf16 v[64:79], v[218:221], v[6:9], v[64:79]
	v_exp_f32_e32 v96, v96
	v_exp_f32_e32 v97, v97
	ds_read_b128 v[218:221], v1 offset:22048
	s_waitcnt lgkmcnt(4)
	v_add_f32_e32 v244, v96, v97
	v_mfma_f32_32x32x16_bf16 v[48:63], v[222:225], v[6:9], v[48:63]
	v_exp_f32_e32 v98, v98
	v_exp_f32_e32 v99, v99
	ds_read_b128 v[222:225], v1 offset:26656
	s_waitcnt lgkmcnt(4)
	v_add_f32_e32 v245, v98, v99
	v_mfma_f32_32x32x16_bf16 v[32:47], v[226:229], v[6:9], v[32:47]
	v_exp_f32_e32 v100, v100
	v_exp_f32_e32 v101, v101
	ds_read_b128 v[226:229], v1 offset:31264
	s_waitcnt lgkmcnt(4)
	v_add_f32_e32 v244, v244, v100
	v_add_f32_e32 v245, v245, v101
	v_mfma_f32_32x32x16_bf16 v[16:31], v[230:233], v[6:9], v[16:31]
	v_exp_f32_e32 v102, v102
	v_exp_f32_e32 v103, v103
	v_add_f32_e32 v244, v244, v102
	v_add_f32_e32 v245, v245, v103
	s_waitcnt lgkmcnt(3)
	v_mfma_f32_32x32x16_bf16 v[64:79], v[2:5], v[10:13], v[64:79]
	v_exp_f32_e32 v104, v104
	v_exp_f32_e32 v105, v105
	v_add_f32_e32 v244, v244, v104
	v_add_f32_e32 v245, v245, v105
	s_barrier
	v_add_u32_e32 v14, s100, v163
	ds_read_b128 v[230:233], v14
	ds_read_b128 v[234:237], v14 offset:32
	ds_read_b128 v[2:5], v14 offset:64
	ds_read_b128 v[248:251], v14 offset:96
	v_add_u32_e32 v246, s98, v193
	v_add_u32_e32 v247, s98, v194
	s_waitcnt lgkmcnt(6)
	v_mfma_f32_32x32x16_bf16 v[48:63], v[218:221], v[10:13], v[48:63]
	v_exp_f32_e32 v106, v106
	v_exp_f32_e32 v107, v107
	ds_read_b128 v[218:221], v14 offset:8704
	s_waitcnt lgkmcnt(6)
	v_add_f32_e32 v244, v244, v106
	v_add_f32_e32 v245, v245, v107
	v_mfma_f32_32x32x16_bf16 v[32:47], v[222:225], v[10:13], v[32:47]
	v_exp_f32_e32 v108, v108
	v_exp_f32_e32 v109, v109
	ds_read_b128 v[222:225], v1 offset:17472
	s_waitcnt lgkmcnt(6)
	v_add_f32_e32 v244, v244, v108
	v_add_f32_e32 v245, v245, v109
	v_mfma_f32_32x32x16_bf16 v[16:31], v[226:229], v[10:13], v[16:31]
	v_exp_f32_e32 v110, v110
	v_exp_f32_e32 v111, v111
	ds_read_b128 v[226:229], v14 offset:8736
	v_add_f32_e32 v244, v244, v110
	v_add_f32_e32 v245, v245, v111
	s_waitcnt vmcnt(0)
	ds_write_b128 v246, v[128:131]
	s_waitcnt lgkmcnt(7)
	v_mfma_f32_32x32x16_bf16 v[80:95], v[230:233], v[112:115], 0
	v_add_f32_e32 v161, v161, v244
	v_cvt_pk_bf16_f32 v144, v96, v97
	v_cvt_pk_bf16_f32 v145, v98, v99
	ds_read_b128 v[230:233], v1 offset:22080
	ds_write_b128 v247, v[132:135] offset:17408
	s_waitcnt lgkmcnt(8)
	v_mfma_f32_32x32x16_bf16 v[80:95], v[234:237], v[116:119], v[80:95]
	v_add_f32_e32 v161, v161, v245
	v_cvt_pk_bf16_f32 v146, v100, v101
	v_cvt_pk_bf16_f32 v147, v102, v103
	ds_read_b128 v[234:237], v14 offset:8768
	ds_write_b128 v246, v[136:139] offset:8704
	s_waitcnt lgkmcnt(9)
	v_mfma_f32_32x32x16_bf16 v[80:95], v[2:5], v[120:123], v[80:95]
	v_cvt_pk_bf16_f32 v150, v104, v105
	v_cvt_pk_bf16_f32 v151, v106, v107
	ds_read_b128 v[2:5], v1 offset:26688
	ds_write_b128 v247, v[140:143] offset:26624
	s_waitcnt lgkmcnt(10)
	v_mfma_f32_32x32x16_bf16 v[80:95], v[248:251], v[124:127], v[80:95]
	v_cvt_pk_bf16_f32 v152, v108, v109
	v_cvt_pk_bf16_f32 v153, v110, v111
	s_cmp_ge_u32 s47, s23
	s_cbranch_scc1 .Lfa_noload_b
	s_lshl_b32 s48, s47, 17
	s_lshl_b32 s4, s47, 7
	s_add_u32 s48, s20, s48
	s_addc_u32 s49, s21, 0
	global_load_dwordx4 v[128:131], v240, s[48:49]
	s_add_u32 s4, s12, s4
	s_addc_u32 s25, s13, 0
	s_mov_b32 s5, s25
	global_load_dwordx4 v[132:135], v242, s[4:5]
	global_load_dwordx4 v[136:139], v241, s[48:49]
	global_load_dwordx4 v[140:143], v243, s[4:5]
	s_mov_b32 s5, 0
